# V^T transposes: one 16-byte store per thread; attention PV: packed f32 adds split; bpost: DPP/permlane wave sums
# speedup vs baseline: 1.0248x; 1.0019x over previous
.LBB0_381:
	s_andn2_saveexec_b64 s[84:85], s[84:85]
	s_cbranch_execz .LBB0_383
	ds_read_b128 v[2:5], v245 offset:31744
	ds_read_b128 v[6:9], v245 offset:38400
	ds_read_b128 v[10:13], v245 offset:31776
	ds_read_b128 v[196:199], v245 offset:38432
	v_add_u32_e32 v0, v204, v247
	s_waitcnt lgkmcnt(3)
	v_mfma_f32_32x32x16_bf16 v[112:127], v[2:5], v[128:131], v[16:31]
	ds_read_b128 v[2:5], v245 offset:31808
	s_waitcnt lgkmcnt(3)
	v_mfma_f32_32x32x16_bf16 v[96:111], v[6:9], v[128:131], v[16:31]
	ds_read_b128 v[6:9], v245 offset:38464
	s_waitcnt lgkmcnt(3)
	v_mfma_f32_32x32x16_bf16 v[112:127], v[10:13], v[132:135], v[112:127]
	ds_read_b128 v[10:13], v245 offset:31840
	s_waitcnt lgkmcnt(3)
	v_mfma_f32_32x32x16_bf16 v[96:111], v[196:199], v[132:135], v[96:111]
	ds_read_b128 v[196:199], v245 offset:38496
	s_waitcnt lgkmcnt(3)
	v_mfma_f32_32x32x16_bf16 v[112:127], v[2:5], v[136:139], v[112:127]
	ds_read_b128 v[2:5], v245 offset:31872
	s_waitcnt lgkmcnt(3)
	v_mfma_f32_32x32x16_bf16 v[96:111], v[6:9], v[136:139], v[96:111]
	ds_read_b128 v[6:9], v245 offset:38528
	s_waitcnt lgkmcnt(3)
	v_mfma_f32_32x32x16_bf16 v[112:127], v[10:13], v[140:143], v[112:127]
	ds_read_b128 v[10:13], v245 offset:31904
	s_waitcnt lgkmcnt(3)
	v_mfma_f32_32x32x16_bf16 v[96:111], v[196:199], v[140:143], v[96:111]
	ds_read_b128 v[196:199], v245 offset:38560
	s_waitcnt lgkmcnt(3)
	v_mfma_f32_32x32x16_bf16 v[112:127], v[2:5], v[144:147], v[112:127]
	s_waitcnt lgkmcnt(2)
	v_mfma_f32_32x32x16_bf16 v[96:111], v[6:9], v[144:147], v[96:111]
	s_waitcnt lgkmcnt(1)
	v_mfma_f32_32x32x16_bf16 v[112:127], v[10:13], v[148:151], v[112:127]
	s_waitcnt lgkmcnt(0)
	v_mfma_f32_32x32x16_bf16 v[96:111], v[196:199], v[148:151], v[96:111]
	ds_read_b128 v[2:5], v0 offset:13312
	s_nop 8
	v_exp_f32_e32 v15, v112
	v_exp_f32_e32 v197, v113
	v_exp_f32_e32 v14, v114
	v_exp_f32_e32 v196, v115
	v_exp_f32_e32 v199, v116
	v_exp_f32_e32 v229, v117
	s_waitcnt lgkmcnt(0)
	v_mfma_f32_32x32x16_bf16 v[80:95], v[2:5], v[180:183], v[80:95]
	ds_read_b128 v[2:5], v0 offset:17920
	v_exp_f32_e32 v198, v118
	v_exp_f32_e32 v228, v119
	s_waitcnt lgkmcnt(0)
	v_mfma_f32_32x32x16_bf16 v[64:79], v[2:5], v[180:183], v[64:79]
	ds_read_b128 v[2:5], v0 offset:22528
	ds_read_b128 v[6:9], v0 offset:27136
	s_waitcnt lgkmcnt(1)
	v_mfma_f32_32x32x16_bf16 v[48:63], v[2:5], v[180:183], v[48:63]
	v_cvt_pk_bf16_f32 v2, v15, v197
	v_cvt_pk_bf16_f32 v3, v14, v196
	v_cvt_pk_bf16_f32 v4, v199, v229
	v_cvt_pk_bf16_f32 v5, v198, v228
	s_waitcnt lgkmcnt(0)
	v_mfma_f32_32x32x16_bf16 v[32:47], v[6:9], v[180:183], v[32:47]
	ds_read_b128 v[6:9], v0 offset:13344
	ds_read_b128 v[10:13], v0 offset:17952
	v_exp_f32_e32 v231, v120
	v_exp_f32_e32 v121, v121
	v_exp_f32_e32 v230, v122
	s_waitcnt lgkmcnt(1)
	v_mfma_f32_32x32x16_bf16 v[80:95], v[6:9], v[184:187], v[80:95]
	v_exp_f32_e32 v120, v123
	v_exp_f32_e32 v123, v124
	v_exp_f32_e32 v125, v125
	v_exp_f32_e32 v122, v126
	v_exp_f32_e32 v124, v127
	s_waitcnt lgkmcnt(0)
	v_mfma_f32_32x32x16_bf16 v[64:79], v[10:13], v[184:187], v[64:79]
	ds_read_b128 v[6:9], v0 offset:22560
	ds_read_b128 v[10:13], v0 offset:27168
	s_waitcnt lgkmcnt(1)
	v_mfma_f32_32x32x16_bf16 v[48:63], v[6:9], v[184:187], v[48:63]
	v_cvt_pk_bf16_f32 v6, v231, v121
	v_cvt_pk_bf16_f32 v7, v230, v120
	v_cvt_pk_bf16_f32 v8, v123, v125
	v_cvt_pk_bf16_f32 v9, v122, v124
	s_waitcnt lgkmcnt(0)
	v_mfma_f32_32x32x16_bf16 v[32:47], v[10:13], v[184:187], v[32:47]
	ds_read_b128 v[10:13], v0 offset:13376
	ds_read_b128 v[112:115], v0 offset:17984
	v_exp_f32_e32 v127, v96
	v_exp_f32_e32 v249, v97
	v_exp_f32_e32 v126, v98
	s_waitcnt lgkmcnt(1)
	v_mfma_f32_32x32x16_bf16 v[80:95], v[10:13], v[188:191], v[80:95]
	v_exp_f32_e32 v248, v99
	v_exp_f32_e32 v251, v100
	v_exp_f32_e32 v233, v101
	v_exp_f32_e32 v250, v102
	v_exp_f32_e32 v232, v103
	s_waitcnt lgkmcnt(0)
	v_mfma_f32_32x32x16_bf16 v[64:79], v[112:115], v[188:191], v[64:79]
	ds_read_b128 v[10:13], v0 offset:22592
	ds_read_b128 v[112:115], v0 offset:27200
	s_waitcnt lgkmcnt(1)
	v_mfma_f32_32x32x16_bf16 v[48:63], v[10:13], v[188:191], v[48:63]
	v_cvt_pk_bf16_f32 v10, v127, v249
	v_cvt_pk_bf16_f32 v11, v126, v248
	v_cvt_pk_bf16_f32 v12, v251, v233
	v_cvt_pk_bf16_f32 v13, v250, v232
	s_waitcnt lgkmcnt(0)
	v_mfma_f32_32x32x16_bf16 v[32:47], v[112:115], v[188:191], v[32:47]
	ds_read_b128 v[96:99], v0 offset:13408
	ds_read_b128 v[100:103], v0 offset:18016
	ds_read_b128 v[112:115], v0 offset:22624
	ds_read_b128 v[116:119], v0 offset:27232
	v_add_f32_e64 v14, v14, v198
	v_add_f32_e64 v15, v15, v199
	s_waitcnt lgkmcnt(3)
	v_mfma_f32_32x32x16_bf16 v[80:95], v[96:99], v[192:195], v[80:95]
	v_exp_f32_e32 v97, v104
	v_exp_f32_e32 v99, v105
	v_exp_f32_e32 v96, v106
	v_exp_f32_e32 v98, v107
	v_add_f32_e32 v14, v222, v14
	v_add_f32_e32 v15, v223, v15
	v_add_f32_e32 v104, v196, v228
	v_add_f32_e32 v105, v197, v229
	v_add_f32_e32 v106, v230, v122
	v_add_f32_e32 v107, v231, v123
	s_waitcnt lgkmcnt(2)
	v_mfma_f32_32x32x16_bf16 v[64:79], v[100:103], v[192:195], v[64:79]
	v_exp_f32_e32 v101, v108
	v_exp_f32_e32 v103, v109
	v_exp_f32_e32 v100, v110
	v_exp_f32_e32 v102, v111
	v_add_f32_e32 v104, v224, v104
	v_add_f32_e32 v105, v225, v105
	v_add_f32_e32 v14, v106, v14
	v_add_f32_e32 v15, v107, v15
	v_add_f32_e32 v106, v120, v124
	v_add_f32_e32 v107, v121, v125
	s_waitcnt lgkmcnt(1)
	v_mfma_f32_32x32x16_bf16 v[48:63], v[112:115], v[192:195], v[48:63]
	v_add_f32_e64 v104, v106, v104
	v_add_f32_e64 v105, v107, v105
	v_add_f32_e64 v106, v126, v250
	v_add_f32_e64 v107, v127, v251
	v_add_f32_e64 v108, v98, v102
	v_add_f32_e64 v109, v99, v103
	v_add_f32_e32 v14, v106, v14
	v_add_f32_e32 v15, v107, v15
	v_add_f32_e32 v106, v248, v232
	v_add_f32_e32 v107, v249, v233
	v_cvt_pk_bf16_f32 v196, v97, v99
	v_add_f32_e32 v104, v106, v104
	v_add_f32_e32 v105, v107, v105
	s_waitcnt lgkmcnt(0)
	v_mfma_f32_32x32x16_bf16 v[32:47], v[116:119], v[192:195], v[32:47]
	v_add_f32_e64 v106, v96, v100
	v_add_f32_e64 v107, v97, v101
	v_add_f32_e64 v224, v108, v104
	v_add_f32_e64 v225, v109, v105
	v_add_f32_e64 v222, v106, v14
	v_add_f32_e64 v223, v107, v15
	v_cvt_pk_bf16_f32 v197, v96, v98
	v_cvt_pk_bf16_f32 v198, v101, v103
	v_cvt_pk_bf16_f32 v199, v100, v102

.LBB0_395:
	s_andn2_saveexec_b64 s[40:41], s[40:41]
	s_cbranch_execz .LBB0_368
	ds_read_b128 v[180:183], v245
	ds_read_b128 v[184:187], v245 offset:6656
	ds_read_b128 v[188:191], v245 offset:32
	ds_read_b128 v[192:195], v245 offset:6688
	s_waitcnt lgkmcnt(3)
	v_mfma_f32_32x32x16_bf16 v[112:127], v[180:183], v[128:131], v[16:31]
	ds_read_b128 v[180:183], v245 offset:64
	s_waitcnt lgkmcnt(3)
	v_mfma_f32_32x32x16_bf16 v[96:111], v[184:187], v[128:131], v[16:31]
	ds_read_b128 v[184:187], v245 offset:6720
	s_waitcnt lgkmcnt(3)
	v_mfma_f32_32x32x16_bf16 v[112:127], v[188:191], v[132:135], v[112:127]
	ds_read_b128 v[188:191], v245 offset:96
	s_waitcnt lgkmcnt(3)
	v_mfma_f32_32x32x16_bf16 v[96:111], v[192:195], v[132:135], v[96:111]
	ds_read_b128 v[192:195], v245 offset:6752
	s_waitcnt lgkmcnt(3)
	v_mfma_f32_32x32x16_bf16 v[112:127], v[180:183], v[136:139], v[112:127]
	ds_read_b128 v[180:183], v245 offset:128
	s_waitcnt lgkmcnt(3)
	v_mfma_f32_32x32x16_bf16 v[96:111], v[184:187], v[136:139], v[96:111]
	ds_read_b128 v[184:187], v245 offset:6784
	s_waitcnt lgkmcnt(3)
	v_mfma_f32_32x32x16_bf16 v[112:127], v[188:191], v[140:143], v[112:127]
	ds_read_b128 v[188:191], v245 offset:160
	s_waitcnt lgkmcnt(3)
	v_mfma_f32_32x32x16_bf16 v[96:111], v[192:195], v[140:143], v[96:111]
	ds_read_b128 v[192:195], v245 offset:6816
	s_waitcnt lgkmcnt(3)
	v_mfma_f32_32x32x16_bf16 v[112:127], v[180:183], v[144:147], v[112:127]
	s_waitcnt lgkmcnt(2)
	v_mfma_f32_32x32x16_bf16 v[96:111], v[184:187], v[144:147], v[96:111]
	s_waitcnt lgkmcnt(1)
	v_mfma_f32_32x32x16_bf16 v[112:127], v[188:191], v[148:151], v[112:127]
	s_waitcnt lgkmcnt(0)
	v_mfma_f32_32x32x16_bf16 v[96:111], v[192:195], v[148:151], v[96:111]
	ds_read_b128 v[180:183], v0 offset:45056
	s_nop 8
	v_exp_f32_e32 v15, v112
	v_exp_f32_e32 v193, v113
	v_exp_f32_e32 v14, v114
	v_exp_f32_e32 v192, v115
	v_exp_f32_e32 v195, v116
	v_exp_f32_e32 v229, v117
	s_waitcnt lgkmcnt(0)
	v_mfma_f32_32x32x16_bf16 v[80:95], v[180:183], v[2:5], v[80:95]
	ds_read_b128 v[180:183], v0 offset:49664
	v_exp_f32_e32 v194, v118
	v_exp_f32_e32 v228, v119
	s_waitcnt lgkmcnt(0)
	v_mfma_f32_32x32x16_bf16 v[64:79], v[180:183], v[2:5], v[64:79]
	ds_read_b128 v[180:183], v0 offset:54272
	ds_read_b128 v[184:187], v0 offset:58880
	s_waitcnt lgkmcnt(1)
	v_mfma_f32_32x32x16_bf16 v[48:63], v[180:183], v[2:5], v[48:63]
	v_cvt_pk_bf16_f32 v180, v15, v193
	v_cvt_pk_bf16_f32 v181, v14, v192
	v_cvt_pk_bf16_f32 v182, v195, v229
	v_cvt_pk_bf16_f32 v183, v194, v228
	s_waitcnt lgkmcnt(0)
	v_mfma_f32_32x32x16_bf16 v[32:47], v[184:187], v[2:5], v[32:47]
	ds_read_b128 v[112:115], v0 offset:45088
	ds_read_b128 v[116:119], v0 offset:49696
	v_exp_f32_e32 v231, v120
	v_exp_f32_e32 v121, v121
	v_exp_f32_e32 v230, v122
	s_waitcnt lgkmcnt(1)
	v_mfma_f32_32x32x16_bf16 v[80:95], v[112:115], v[6:9], v[80:95]
	v_exp_f32_e32 v120, v123
	v_exp_f32_e32 v123, v124
	v_exp_f32_e32 v125, v125
	v_exp_f32_e32 v122, v126
	v_exp_f32_e32 v124, v127
	v_cvt_pk_bf16_f32 v184, v231, v121
	v_cvt_pk_bf16_f32 v185, v230, v120
	s_waitcnt lgkmcnt(0)
	v_mfma_f32_32x32x16_bf16 v[64:79], v[116:119], v[6:9], v[64:79]
	ds_read_b128 v[112:115], v0 offset:54304
	ds_read_b128 v[116:119], v0 offset:58912
	v_cvt_pk_bf16_f32 v186, v123, v125
	v_cvt_pk_bf16_f32 v187, v122, v124
	s_waitcnt lgkmcnt(1)
	v_mfma_f32_32x32x16_bf16 v[48:63], v[112:115], v[6:9], v[48:63]
	s_waitcnt lgkmcnt(0)
	v_mfma_f32_32x32x16_bf16 v[32:47], v[116:119], v[6:9], v[32:47]
	ds_read_b128 v[112:115], v0 offset:45120
	ds_read_b128 v[116:119], v0 offset:49728
	v_exp_f32_e32 v127, v96
	v_exp_f32_e32 v233, v97
	v_exp_f32_e32 v126, v98
	s_waitcnt lgkmcnt(1)
	v_mfma_f32_32x32x16_bf16 v[80:95], v[112:115], v[10:13], v[80:95]
	v_exp_f32_e32 v232, v99
	v_exp_f32_e32 v249, v100
	v_exp_f32_e32 v251, v101
	v_exp_f32_e32 v248, v102
	v_exp_f32_e32 v250, v103
	v_cvt_pk_bf16_f32 v188, v127, v233
	v_cvt_pk_bf16_f32 v189, v126, v232
	s_waitcnt lgkmcnt(0)
	v_mfma_f32_32x32x16_bf16 v[64:79], v[116:119], v[10:13], v[64:79]
	ds_read_b128 v[112:115], v0 offset:54336
	ds_read_b128 v[116:119], v0 offset:58944
	v_cvt_pk_bf16_f32 v190, v249, v251
	v_cvt_pk_bf16_f32 v191, v248, v250
	s_waitcnt lgkmcnt(1)
	v_mfma_f32_32x32x16_bf16 v[48:63], v[112:115], v[10:13], v[48:63]
	s_waitcnt lgkmcnt(0)
	v_mfma_f32_32x32x16_bf16 v[32:47], v[116:119], v[10:13], v[32:47]
	ds_read_b128 v[96:99], v0 offset:45152
	ds_read_b128 v[100:103], v0 offset:49760
	ds_read_b128 v[112:115], v0 offset:54368
	ds_read_b128 v[116:119], v0 offset:58976
	v_add_f32_e64 v14, v14, v194
	v_add_f32_e64 v15, v15, v195
	s_waitcnt lgkmcnt(3)
	v_mfma_f32_32x32x16_bf16 v[80:95], v[96:99], v[196:199], v[80:95]
	v_exp_f32_e32 v97, v104
	v_exp_f32_e32 v99, v105
	v_exp_f32_e32 v96, v106
	v_exp_f32_e32 v98, v107
	v_add_f32_e32 v14, v222, v14
	v_add_f32_e32 v15, v223, v15
	v_add_f32_e32 v104, v192, v228
	v_add_f32_e32 v105, v193, v229
	v_add_f32_e32 v106, v230, v122
	v_add_f32_e32 v107, v231, v123
	s_waitcnt lgkmcnt(2)
	v_mfma_f32_32x32x16_bf16 v[64:79], v[100:103], v[196:199], v[64:79]
	v_exp_f32_e32 v101, v108
	v_exp_f32_e32 v103, v109
	v_exp_f32_e32 v100, v110
	v_exp_f32_e32 v102, v111
	v_add_f32_e32 v104, v224, v104
	v_add_f32_e32 v105, v225, v105
	v_add_f32_e32 v14, v106, v14
	v_add_f32_e32 v15, v107, v15
	v_add_f32_e32 v106, v120, v124
	v_add_f32_e32 v107, v121, v125
	s_waitcnt lgkmcnt(1)
	v_mfma_f32_32x32x16_bf16 v[48:63], v[112:115], v[196:199], v[48:63]
	v_add_f32_e64 v104, v106, v104
	v_add_f32_e64 v105, v107, v105
	v_add_f32_e64 v106, v126, v248
	v_add_f32_e64 v107, v127, v249
	v_add_f32_e64 v108, v98, v102
	v_add_f32_e64 v109, v99, v103
	v_add_f32_e32 v14, v106, v14
	v_add_f32_e32 v15, v107, v15
	v_add_f32_e32 v106, v232, v250
	v_add_f32_e32 v107, v233, v251
	v_cvt_pk_bf16_f32 v192, v97, v99
	v_add_f32_e32 v104, v106, v104
	v_add_f32_e32 v105, v107, v105
	s_waitcnt lgkmcnt(0)
	v_mfma_f32_32x32x16_bf16 v[32:47], v[116:119], v[196:199], v[32:47]
	v_add_f32_e64 v106, v96, v100
	v_add_f32_e64 v107, v97, v101
	v_add_f32_e64 v224, v108, v104
	v_add_f32_e64 v225, v109, v105
	v_add_f32_e64 v222, v106, v14
	v_add_f32_e64 v223, v107, v15
	v_cvt_pk_bf16_f32 v193, v96, v98
	v_cvt_pk_bf16_f32 v194, v101, v103
	v_cvt_pk_bf16_f32 v195, v100, v102
	s_branch .LBB0_368

.LBB0_415:
	s_andn2_saveexec_b64 s[84:85], s[84:85]
	s_cbranch_execz .LBB0_417
	ds_read_b128 v[2:5], v220 offset:31744
	ds_read_b128 v[6:9], v220 offset:36352
	ds_read_b128 v[10:13], v220 offset:31776
	ds_read_b128 v[184:187], v220 offset:36384
	v_add_u32_e32 v0, v190, v222
	s_waitcnt lgkmcnt(3)
	v_mfma_f32_32x32x16_bf16 v[112:127], v[2:5], v[128:131], v[16:31]
	ds_read_b128 v[2:5], v220 offset:31808
	s_waitcnt lgkmcnt(3)
	v_mfma_f32_32x32x16_bf16 v[96:111], v[6:9], v[128:131], v[16:31]
	ds_read_b128 v[6:9], v220 offset:36416
	s_waitcnt lgkmcnt(3)
	v_mfma_f32_32x32x16_bf16 v[112:127], v[10:13], v[132:135], v[112:127]
	ds_read_b128 v[10:13], v220 offset:31840
	s_waitcnt lgkmcnt(3)
	v_mfma_f32_32x32x16_bf16 v[96:111], v[184:187], v[132:135], v[96:111]
	ds_read_b128 v[184:187], v220 offset:36448
	s_waitcnt lgkmcnt(3)
	v_mfma_f32_32x32x16_bf16 v[112:127], v[2:5], v[136:139], v[112:127]
	s_waitcnt lgkmcnt(2)
	v_mfma_f32_32x32x16_bf16 v[96:111], v[6:9], v[136:139], v[96:111]
	s_waitcnt lgkmcnt(1)
	v_mfma_f32_32x32x16_bf16 v[112:127], v[10:13], v[140:143], v[112:127]
	s_waitcnt lgkmcnt(0)
	v_mfma_f32_32x32x16_bf16 v[96:111], v[184:187], v[140:143], v[96:111]
	ds_read_b128 v[2:5], v0 offset:13312
	s_nop 8
	v_exp_f32_e32 v15, v112
	v_exp_f32_e32 v185, v113
	v_exp_f32_e32 v14, v114
	v_exp_f32_e32 v184, v115
	v_exp_f32_e32 v187, v116
	v_exp_f32_e32 v225, v117
	s_waitcnt lgkmcnt(0)
	v_mfma_f32_32x32x16_bf16 v[80:95], v[2:5], v[168:171], v[80:95]
	ds_read_b128 v[2:5], v0 offset:17920
	v_exp_f32_e32 v186, v118
	v_exp_f32_e32 v224, v119
	s_waitcnt lgkmcnt(0)
	v_mfma_f32_32x32x16_bf16 v[64:79], v[2:5], v[168:171], v[64:79]
	ds_read_b128 v[2:5], v0 offset:22528
	ds_read_b128 v[6:9], v0 offset:27136
	s_waitcnt lgkmcnt(1)
	v_mfma_f32_32x32x16_bf16 v[48:63], v[2:5], v[168:171], v[48:63]
	v_cvt_pk_bf16_f32 v2, v15, v185
	v_cvt_pk_bf16_f32 v3, v14, v184
	v_cvt_pk_bf16_f32 v4, v187, v225
	v_cvt_pk_bf16_f32 v5, v186, v224
	s_waitcnt lgkmcnt(0)
	v_mfma_f32_32x32x16_bf16 v[32:47], v[6:9], v[168:171], v[32:47]
	ds_read_b128 v[6:9], v0 offset:13344
	ds_read_b128 v[10:13], v0 offset:17952
	v_exp_f32_e32 v229, v120
	v_exp_f32_e32 v121, v121
	v_exp_f32_e32 v228, v122
	s_waitcnt lgkmcnt(1)
	v_mfma_f32_32x32x16_bf16 v[80:95], v[6:9], v[172:175], v[80:95]
	v_exp_f32_e32 v120, v123
	v_exp_f32_e32 v123, v124
	v_exp_f32_e32 v125, v125
	v_exp_f32_e32 v122, v126
	v_exp_f32_e32 v124, v127
	s_waitcnt lgkmcnt(0)
	v_mfma_f32_32x32x16_bf16 v[64:79], v[10:13], v[172:175], v[64:79]
	ds_read_b128 v[6:9], v0 offset:22560
	ds_read_b128 v[10:13], v0 offset:27168
	s_waitcnt lgkmcnt(1)
	v_mfma_f32_32x32x16_bf16 v[48:63], v[6:9], v[172:175], v[48:63]
	v_cvt_pk_bf16_f32 v6, v229, v121
	v_cvt_pk_bf16_f32 v7, v228, v120
	v_cvt_pk_bf16_f32 v8, v123, v125
	v_cvt_pk_bf16_f32 v9, v122, v124
	s_waitcnt lgkmcnt(0)
	v_mfma_f32_32x32x16_bf16 v[32:47], v[10:13], v[172:175], v[32:47]
	ds_read_b128 v[10:13], v0 offset:13376
	ds_read_b128 v[112:115], v0 offset:17984
	v_exp_f32_e32 v127, v96
	v_exp_f32_e32 v231, v97
	v_exp_f32_e32 v126, v98
	s_waitcnt lgkmcnt(1)
	v_mfma_f32_32x32x16_bf16 v[80:95], v[10:13], v[176:179], v[80:95]
	v_exp_f32_e32 v230, v99
	v_exp_f32_e32 v237, v100
	v_exp_f32_e32 v239, v101
	v_exp_f32_e32 v236, v102
	v_exp_f32_e32 v238, v103
	s_waitcnt lgkmcnt(0)
	v_mfma_f32_32x32x16_bf16 v[64:79], v[112:115], v[176:179], v[64:79]
	ds_read_b128 v[10:13], v0 offset:22592
	ds_read_b128 v[112:115], v0 offset:27200
	s_waitcnt lgkmcnt(1)
	v_mfma_f32_32x32x16_bf16 v[48:63], v[10:13], v[176:179], v[48:63]
	v_cvt_pk_bf16_f32 v10, v127, v231
	v_cvt_pk_bf16_f32 v11, v126, v230
	v_cvt_pk_bf16_f32 v12, v237, v239
	v_cvt_pk_bf16_f32 v13, v236, v238
	s_waitcnt lgkmcnt(0)
	v_mfma_f32_32x32x16_bf16 v[32:47], v[112:115], v[176:179], v[32:47]
	ds_read_b128 v[96:99], v0 offset:13408
	ds_read_b128 v[100:103], v0 offset:18016
	ds_read_b128 v[112:115], v0 offset:22624
	ds_read_b128 v[116:119], v0 offset:27232
	v_add_f32_e64 v14, v14, v186
	v_add_f32_e64 v15, v15, v187
	s_waitcnt lgkmcnt(3)
	v_mfma_f32_32x32x16_bf16 v[80:95], v[96:99], v[180:183], v[80:95]
	v_exp_f32_e32 v97, v104
	v_exp_f32_e32 v99, v105
	v_exp_f32_e32 v96, v106
	v_exp_f32_e32 v98, v107
	v_add_f32_e32 v14, v208, v14
	v_add_f32_e32 v15, v209, v15
	v_add_f32_e32 v104, v184, v224
	v_add_f32_e32 v105, v185, v225
	v_add_f32_e32 v106, v228, v122
	v_add_f32_e32 v107, v229, v123
	s_waitcnt lgkmcnt(2)
	v_mfma_f32_32x32x16_bf16 v[64:79], v[100:103], v[180:183], v[64:79]
	v_exp_f32_e32 v101, v108
	v_exp_f32_e32 v103, v109
	v_exp_f32_e32 v100, v110
	v_exp_f32_e32 v102, v111
	v_add_f32_e32 v104, v210, v104
	v_add_f32_e32 v105, v211, v105
	v_add_f32_e32 v14, v106, v14
	v_add_f32_e32 v15, v107, v15
	v_add_f32_e32 v106, v120, v124
	v_add_f32_e32 v107, v121, v125
	s_waitcnt lgkmcnt(1)
	v_mfma_f32_32x32x16_bf16 v[48:63], v[112:115], v[180:183], v[48:63]
	v_add_f32_e64 v104, v106, v104
	v_add_f32_e64 v105, v107, v105
	v_add_f32_e64 v106, v126, v236
	v_add_f32_e64 v107, v127, v237
	v_add_f32_e64 v108, v98, v102
	v_add_f32_e64 v109, v99, v103
	v_add_f32_e32 v14, v106, v14
	v_add_f32_e32 v15, v107, v15
	v_add_f32_e32 v106, v230, v238
	v_add_f32_e32 v107, v231, v239
	v_cvt_pk_bf16_f32 v184, v97, v99
	v_add_f32_e32 v104, v106, v104
	v_add_f32_e32 v105, v107, v105
	s_waitcnt lgkmcnt(0)
	v_mfma_f32_32x32x16_bf16 v[32:47], v[116:119], v[180:183], v[32:47]
	v_add_f32_e64 v106, v96, v100
	v_add_f32_e64 v107, v97, v101
	v_add_f32_e64 v210, v108, v104
	v_add_f32_e64 v211, v109, v105
	v_add_f32_e64 v208, v106, v14
	v_add_f32_e64 v209, v107, v15
	v_cvt_pk_bf16_f32 v185, v96, v98
	v_cvt_pk_bf16_f32 v186, v101, v103
	v_cvt_pk_bf16_f32 v187, v100, v102

.LBB0_429:
	s_andn2_saveexec_b64 s[40:41], s[40:41]
	s_cbranch_execz .LBB0_402
	ds_read_b128 v[168:171], v220
	ds_read_b128 v[172:175], v220 offset:4608
	ds_read_b128 v[176:179], v220 offset:32
	ds_read_b128 v[180:183], v220 offset:4640
	s_waitcnt lgkmcnt(3)
	v_mfma_f32_32x32x16_bf16 v[112:127], v[168:171], v[128:131], v[16:31]
	ds_read_b128 v[168:171], v220 offset:64
	s_waitcnt lgkmcnt(3)
	v_mfma_f32_32x32x16_bf16 v[96:111], v[172:175], v[128:131], v[16:31]
	ds_read_b128 v[172:175], v220 offset:4672
	s_waitcnt lgkmcnt(3)
	v_mfma_f32_32x32x16_bf16 v[112:127], v[176:179], v[132:135], v[112:127]
	ds_read_b128 v[176:179], v220 offset:96
	s_waitcnt lgkmcnt(3)
	v_mfma_f32_32x32x16_bf16 v[96:111], v[180:183], v[132:135], v[96:111]
	ds_read_b128 v[180:183], v220 offset:4704
	s_waitcnt lgkmcnt(3)
	v_mfma_f32_32x32x16_bf16 v[112:127], v[168:171], v[136:139], v[112:127]
	s_waitcnt lgkmcnt(2)
	v_mfma_f32_32x32x16_bf16 v[96:111], v[172:175], v[136:139], v[96:111]
	s_waitcnt lgkmcnt(1)
	v_mfma_f32_32x32x16_bf16 v[112:127], v[176:179], v[140:143], v[112:127]
	s_waitcnt lgkmcnt(0)
	v_mfma_f32_32x32x16_bf16 v[96:111], v[180:183], v[140:143], v[96:111]
	ds_read_b128 v[168:171], v0 offset:45056
	s_nop 8
	v_exp_f32_e32 v15, v112
	v_exp_f32_e32 v181, v113
	v_exp_f32_e32 v14, v114
	v_exp_f32_e32 v180, v115
	v_exp_f32_e32 v183, v116
	v_exp_f32_e32 v225, v117
	s_waitcnt lgkmcnt(0)
	v_mfma_f32_32x32x16_bf16 v[80:95], v[168:171], v[2:5], v[80:95]
	ds_read_b128 v[168:171], v0 offset:49664
	v_exp_f32_e32 v182, v118
	v_exp_f32_e32 v224, v119
	s_waitcnt lgkmcnt(0)
	v_mfma_f32_32x32x16_bf16 v[64:79], v[168:171], v[2:5], v[64:79]
	ds_read_b128 v[168:171], v0 offset:54272
	ds_read_b128 v[172:175], v0 offset:58880
	s_waitcnt lgkmcnt(1)
	v_mfma_f32_32x32x16_bf16 v[48:63], v[168:171], v[2:5], v[48:63]
	v_cvt_pk_bf16_f32 v168, v15, v181
	v_cvt_pk_bf16_f32 v169, v14, v180
	v_cvt_pk_bf16_f32 v170, v183, v225
	v_cvt_pk_bf16_f32 v171, v182, v224
	s_waitcnt lgkmcnt(0)
	v_mfma_f32_32x32x16_bf16 v[32:47], v[172:175], v[2:5], v[32:47]
	ds_read_b128 v[112:115], v0 offset:45088
	ds_read_b128 v[116:119], v0 offset:49696
	v_exp_f32_e32 v229, v120
	v_exp_f32_e32 v121, v121
	v_exp_f32_e32 v228, v122
	s_waitcnt lgkmcnt(1)
	v_mfma_f32_32x32x16_bf16 v[80:95], v[112:115], v[6:9], v[80:95]
	v_exp_f32_e32 v120, v123
	v_exp_f32_e32 v123, v124
	v_exp_f32_e32 v125, v125
	v_exp_f32_e32 v122, v126
	v_exp_f32_e32 v124, v127
	v_cvt_pk_bf16_f32 v172, v229, v121
	v_cvt_pk_bf16_f32 v173, v228, v120
	s_waitcnt lgkmcnt(0)
	v_mfma_f32_32x32x16_bf16 v[64:79], v[116:119], v[6:9], v[64:79]
	ds_read_b128 v[112:115], v0 offset:54304
	ds_read_b128 v[116:119], v0 offset:58912
	v_cvt_pk_bf16_f32 v174, v123, v125
	v_cvt_pk_bf16_f32 v175, v122, v124
	s_waitcnt lgkmcnt(1)
	v_mfma_f32_32x32x16_bf16 v[48:63], v[112:115], v[6:9], v[48:63]
	s_waitcnt lgkmcnt(0)
	v_mfma_f32_32x32x16_bf16 v[32:47], v[116:119], v[6:9], v[32:47]
	ds_read_b128 v[112:115], v0 offset:45120
	ds_read_b128 v[116:119], v0 offset:49728
	v_exp_f32_e32 v127, v96
	v_exp_f32_e32 v231, v97
	v_exp_f32_e32 v126, v98
	s_waitcnt lgkmcnt(1)
	v_mfma_f32_32x32x16_bf16 v[80:95], v[112:115], v[10:13], v[80:95]
	v_exp_f32_e32 v230, v99
	v_exp_f32_e32 v237, v100
	v_exp_f32_e32 v239, v101
	v_exp_f32_e32 v236, v102
	v_exp_f32_e32 v238, v103
	v_cvt_pk_bf16_f32 v176, v127, v231
	v_cvt_pk_bf16_f32 v177, v126, v230
	s_waitcnt lgkmcnt(0)
	v_mfma_f32_32x32x16_bf16 v[64:79], v[116:119], v[10:13], v[64:79]
	ds_read_b128 v[112:115], v0 offset:54336
	ds_read_b128 v[116:119], v0 offset:58944
	v_cvt_pk_bf16_f32 v178, v237, v239
	v_cvt_pk_bf16_f32 v179, v236, v238
	s_waitcnt lgkmcnt(1)
	v_mfma_f32_32x32x16_bf16 v[48:63], v[112:115], v[10:13], v[48:63]
	s_waitcnt lgkmcnt(0)
	v_mfma_f32_32x32x16_bf16 v[32:47], v[116:119], v[10:13], v[32:47]
	ds_read_b128 v[96:99], v0 offset:45152
	ds_read_b128 v[100:103], v0 offset:49760
	ds_read_b128 v[112:115], v0 offset:54368
	ds_read_b128 v[116:119], v0 offset:58976
	v_add_f32_e64 v14, v14, v182
	v_add_f32_e64 v15, v15, v183
	s_waitcnt lgkmcnt(3)
	v_mfma_f32_32x32x16_bf16 v[80:95], v[96:99], v[184:187], v[80:95]
	v_exp_f32_e32 v97, v104
	v_exp_f32_e32 v99, v105
	v_exp_f32_e32 v96, v106
	v_exp_f32_e32 v98, v107
	v_add_f32_e32 v14, v208, v14
	v_add_f32_e32 v15, v209, v15
	v_add_f32_e32 v104, v180, v224
	v_add_f32_e32 v105, v181, v225
	v_add_f32_e32 v106, v228, v122
	v_add_f32_e32 v107, v229, v123
	s_waitcnt lgkmcnt(2)
	v_mfma_f32_32x32x16_bf16 v[64:79], v[100:103], v[184:187], v[64:79]
	v_exp_f32_e32 v101, v108
	v_exp_f32_e32 v103, v109
	v_exp_f32_e32 v100, v110
	v_exp_f32_e32 v102, v111
	v_add_f32_e32 v104, v210, v104
	v_add_f32_e32 v105, v211, v105
	v_add_f32_e32 v14, v106, v14
	v_add_f32_e32 v15, v107, v15
	v_add_f32_e32 v106, v120, v124
	v_add_f32_e32 v107, v121, v125
	s_waitcnt lgkmcnt(1)
	v_mfma_f32_32x32x16_bf16 v[48:63], v[112:115], v[184:187], v[48:63]
	v_add_f32_e64 v104, v106, v104
	v_add_f32_e64 v105, v107, v105
	v_add_f32_e64 v106, v126, v236
	v_add_f32_e64 v107, v127, v237
	v_add_f32_e64 v108, v98, v102
	v_add_f32_e64 v109, v99, v103
	v_add_f32_e32 v14, v106, v14
	v_add_f32_e32 v15, v107, v15
	v_add_f32_e32 v106, v230, v238
	v_add_f32_e32 v107, v231, v239
	v_cvt_pk_bf16_f32 v180, v97, v99
	v_add_f32_e32 v104, v106, v104
	v_add_f32_e32 v105, v107, v105
	s_waitcnt lgkmcnt(0)
	v_mfma_f32_32x32x16_bf16 v[32:47], v[116:119], v[184:187], v[32:47]
	v_add_f32_e64 v106, v96, v100
	v_add_f32_e64 v107, v97, v101
	v_add_f32_e64 v210, v108, v104
	v_add_f32_e64 v211, v109, v105
	v_add_f32_e64 v208, v106, v14
	v_add_f32_e64 v209, v107, v15
	v_cvt_pk_bf16_f32 v181, v96, v98
	v_cvt_pk_bf16_f32 v182, v101, v103
	v_cvt_pk_bf16_f32 v183, v100, v102
	s_branch .LBB0_402

; DI float bf2f(unsigned h) { return __uint_as_float(h << 16); }
; DI float wave_sum(float v) {
; #pragma unroll
;   for (int o = 32; o >= 1; o >>= 1) v += __shfl_xor(v, o);
;   return v;
; DI void bpost_item(const Params& p, int l, int b, int item, bf16_t* lds) {
;     ...
;         float e0, e1;
;         if (qk == 0) { e0 = bf2f(YQ[(size_t)t * 384 + h * 96 + lane]) * rq; e1 = lane < 32 ? bf2f(YQ[(size_t)t * 384 + h * 96 + 64 + lane]) * rq : 0.f; }
;         else { e0 = bf2f(YKV[(size_t)t * 768 + h * 192 + lane]) * rkv; e1 = kr; }
;         float ss = wave_sum(e0 * e0 + e1 * e1);
;         const float r = rsqrtf(ss * (1.f / 96.f) + EPS);
;         const float* nw = (qk == 0 ? p.mqn : p.mkn) + l * 96;
;         float n0 = e0 * r * nw[lane];
;         float n1 = lane < 32 ? e1 * r * nw[64 + lane] : 0.f;
.LBB0_463:
	s_or_b64 exec, exec, s[0:1]
	s_waitcnt vmcnt(0)
	v_lshlrev_b32_e32 v17, 16, v17
	v_mul_f32_e32 v24, v39, v17
	v_pk_mul_f32 v[18:19], v[24:25], v[24:25]
	s_nop 0
	v_add_f32_e32 v17, v18, v19
	s_nop 1
	v_add_f32_dpp v17, v17, v17 quad_perm:[1,0,3,2] row_mask:0xf bank_mask:0xf
	s_nop 1
	v_add_f32_dpp v17, v17, v17 quad_perm:[2,3,0,1] row_mask:0xf bank_mask:0xf
	s_nop 1
	v_add_f32_dpp v17, v17, v17 row_half_mirror row_mask:0xf bank_mask:0xf
	s_nop 1
	v_add_f32_dpp v17, v17, v17 row_mirror row_mask:0xf bank_mask:0xf
	v_mov_b32_e32 v18, v17
	s_nop 1
	v_permlane16_swap_b32_e32 v17, v18
	s_nop 1
	v_add_f32_e32 v17, v17, v18
	v_mov_b32_e32 v18, v17
	s_nop 1
	v_permlane32_swap_b32_e32 v17, v18
	s_nop 1
	v_add_f32_e32 v17, v17, v18
	v_fmamk_f32 v17, v17, 0x3c2aaaab, v200
	v_mul_f32_e32 v18, 0x4b800000, v17
	v_cmp_gt_f32_e32 vcc, s58, v17
	s_nop 1
	v_cndmask_b32_e32 v17, v17, v18, vcc
	v_rsq_f32_e32 v17, v17
	s_nop 0
	v_mul_f32_e32 v18, 0x45800000, v17
	v_cndmask_b32_e32 v18, v17, v18, vcc
	v_mov_b32_e32 v17, 0
	s_and_saveexec_b64 s[0:1], s[40:41]
	s_cbranch_execz .LBB0_465
	v_mov_b32_e32 v17, v90
	v_mul_f32_e32 v19, v25, v18
	v_mul_f32_e32 v17, v19, v17

; DI float bf2f(unsigned h) { return __uint_as_float(h << 16); }
; DI float wave_sum(float v) {
; #pragma unroll
;   for (int o = 32; o >= 1; o >>= 1) v += __shfl_xor(v, o);
;   return v;
; DI void bpost_item(const Params& p, int l, int b, int item, bf16_t* lds) {
;     ...
;         float e0, e1;
;         if (qk == 0) { e0 = bf2f(YQ[(size_t)t * 384 + h * 96 + lane]) * rq; e1 = lane < 32 ? bf2f(YQ[(size_t)t * 384 + h * 96 + 64 + lane]) * rq : 0.f; }
;         else { e0 = bf2f(YKV[(size_t)t * 768 + h * 192 + lane]) * rkv; e1 = kr; }
;         float ss = wave_sum(e0 * e0 + e1 * e1);
;         const float r = rsqrtf(ss * (1.f / 96.f) + EPS);
;         const float* nw = (qk == 0 ? p.mqn : p.mkn) + l * 96;
;         float n0 = e0 * r * nw[lane];
;         float n1 = lane < 32 ? e1 * r * nw[64 + lane] : 0.f;
.LBB0_467:
	s_or_b64 exec, exec, s[0:1]
	v_lshl_add_u64 v[22:23], v[22:23], 1, v[4:5]
	v_mov_b32_e32 v17, v98
	v_lshlrev_b32_e32 v17, 16, v17
	v_mul_f32_e32 v17, v38, v17
	s_waitcnt lgkmcnt(0)
	v_pk_mul_f32 v[24:25], v[16:17], v[16:17]
	s_nop 0
	v_add_f32_e32 v25, v24, v25
	s_nop 1
	v_add_f32_dpp v25, v25, v25 quad_perm:[1,0,3,2] row_mask:0xf bank_mask:0xf
	s_nop 1
	v_add_f32_dpp v25, v25, v25 quad_perm:[2,3,0,1] row_mask:0xf bank_mask:0xf
	s_nop 1
	v_add_f32_dpp v25, v25, v25 row_half_mirror row_mask:0xf bank_mask:0xf
	s_nop 1
	v_add_f32_dpp v25, v25, v25 row_mirror row_mask:0xf bank_mask:0xf
	v_mov_b32_e32 v26, v25
	s_nop 1
	v_permlane16_swap_b32_e32 v25, v26
	s_nop 1
	v_add_f32_e32 v25, v25, v26
	v_mov_b32_e32 v26, v25
	s_nop 1
	v_permlane32_swap_b32_e32 v25, v26
	s_nop 1
	v_add_f32_e32 v25, v25, v26
	v_fmamk_f32 v25, v25, 0x3c2aaaab, v200
	v_mul_f32_e32 v26, 0x4b800000, v25
	v_cmp_gt_f32_e32 vcc, s58, v25
	s_nop 1
	v_cndmask_b32_e32 v25, v25, v26, vcc
	v_rsq_f32_e32 v25, v25
	s_nop 0
	v_mul_f32_e32 v26, 0x45800000, v25
	v_cndmask_b32_e32 v26, v25, v26, vcc
	v_mov_b32_e32 v25, 0
	s_and_saveexec_b64 s[0:1], s[40:41]
	s_cbranch_execz .LBB0_469
	v_mov_b32_e32 v25, v91
	v_mul_f32_e32 v27, v16, v26
	v_mul_f32_e32 v25, v27, v25

; DI float bf2f(unsigned h) { return __uint_as_float(h << 16); }
; DI float wave_sum(float v) {
; #pragma unroll
;   for (int o = 32; o >= 1; o >>= 1) v += __shfl_xor(v, o);
;   return v;
; DI void bpost_item(const Params& p, int l, int b, int item, bf16_t* lds) {
;     ...
;         float e0, e1;
;         if (qk == 0) { e0 = bf2f(YQ[(size_t)t * 384 + h * 96 + lane]) * rq; e1 = lane < 32 ? bf2f(YQ[(size_t)t * 384 + h * 96 + 64 + lane]) * rq : 0.f; }
;         else { e0 = bf2f(YKV[(size_t)t * 768 + h * 192 + lane]) * rkv; e1 = kr; }
;         float ss = wave_sum(e0 * e0 + e1 * e1);
;         const float r = rsqrtf(ss * (1.f / 96.f) + EPS);
;         const float* nw = (qk == 0 ? p.mqn : p.mkn) + l * 96;
;         float n0 = e0 * r * nw[lane];
;         float n1 = lane < 32 ? e1 * r * nw[64 + lane] : 0.f;
.LBB0_473:
	s_or_b64 exec, exec, s[0:1]
	s_waitcnt vmcnt(0)
	v_lshlrev_b32_e32 v25, 16, v25
	v_mul_f32_e32 v26, v39, v25
	v_pk_mul_f32 v[40:41], v[26:27], v[26:27]
	s_nop 0
	v_add_f32_e32 v25, v40, v41
	s_nop 1
	v_add_f32_dpp v25, v25, v25 quad_perm:[1,0,3,2] row_mask:0xf bank_mask:0xf
	s_nop 1
	v_add_f32_dpp v25, v25, v25 quad_perm:[2,3,0,1] row_mask:0xf bank_mask:0xf
	s_nop 1
	v_add_f32_dpp v25, v25, v25 row_half_mirror row_mask:0xf bank_mask:0xf
	s_nop 1
	v_add_f32_dpp v25, v25, v25 row_mirror row_mask:0xf bank_mask:0xf
	v_mov_b32_e32 v40, v25
	s_nop 1
	v_permlane16_swap_b32_e32 v25, v40
	s_nop 1
	v_add_f32_e32 v25, v25, v40
	v_mov_b32_e32 v40, v25
	s_nop 1
	v_permlane32_swap_b32_e32 v25, v40
	s_nop 1
	v_add_f32_e32 v25, v25, v40
	v_fmamk_f32 v25, v25, 0x3c2aaaab, v200
	v_mul_f32_e32 v40, 0x4b800000, v25
	v_cmp_gt_f32_e32 vcc, s58, v25
	s_nop 1
	v_cndmask_b32_e32 v25, v25, v40, vcc
	v_rsq_f32_e32 v25, v25
	s_nop 0
	v_mul_f32_e32 v40, 0x45800000, v25
	v_cndmask_b32_e32 v25, v25, v40, vcc
	s_and_saveexec_b64 s[0:1], s[40:41]
	s_cbranch_execz .LBB0_475
	v_mov_b32_e32 v17, v90
	v_mul_f32_e32 v27, v27, v25
	v_mul_f32_e32 v17, v27, v17

; DI float bf2f(unsigned h) { return __uint_as_float(h << 16); }
; DI float wave_sum(float v) {
; #pragma unroll
;   for (int o = 32; o >= 1; o >>= 1) v += __shfl_xor(v, o);
;   return v;
; DI void bpost_item(const Params& p, int l, int b, int item, bf16_t* lds) {
;     ...
;         float e0, e1;
;         if (qk == 0) { e0 = bf2f(YQ[(size_t)t * 384 + h * 96 + lane]) * rq; e1 = lane < 32 ? bf2f(YQ[(size_t)t * 384 + h * 96 + 64 + lane]) * rq : 0.f; }
;         else { e0 = bf2f(YKV[(size_t)t * 768 + h * 192 + lane]) * rkv; e1 = kr; }
;         float ss = wave_sum(e0 * e0 + e1 * e1);
;         const float r = rsqrtf(ss * (1.f / 96.f) + EPS);
;         const float* nw = (qk == 0 ? p.mqn : p.mkn) + l * 96;
;         float n0 = e0 * r * nw[lane];
;         float n1 = lane < 32 ? e1 * r * nw[64 + lane] : 0.f;
.LBB0_477:
	s_or_b64 exec, exec, s[0:1]
	v_mov_b32_e32 v17, v99
	v_lshlrev_b32_e32 v17, 16, v17
	v_mul_f32_e32 v17, v38, v17
	s_waitcnt lgkmcnt(0)
	v_fma_f32 v25, v17, v17, v24
	s_nop 1
	v_add_f32_dpp v25, v25, v25 quad_perm:[1,0,3,2] row_mask:0xf bank_mask:0xf
	s_nop 1
	v_add_f32_dpp v25, v25, v25 quad_perm:[2,3,0,1] row_mask:0xf bank_mask:0xf
	s_nop 1
	v_add_f32_dpp v25, v25, v25 row_half_mirror row_mask:0xf bank_mask:0xf
	s_nop 1
	v_add_f32_dpp v25, v25, v25 row_mirror row_mask:0xf bank_mask:0xf
	v_mov_b32_e32 v26, v25
	s_nop 1
	v_permlane16_swap_b32_e32 v25, v26
	s_nop 1
	v_add_f32_e32 v25, v25, v26
	v_mov_b32_e32 v26, v25
	s_nop 1
	v_permlane32_swap_b32_e32 v25, v26
	s_nop 1
	v_add_f32_e32 v25, v25, v26
	v_fmamk_f32 v25, v25, 0x3c2aaaab, v200
	v_mul_f32_e32 v26, 0x4b800000, v25
	v_cmp_gt_f32_e32 vcc, s58, v25
	s_nop 1
	v_cndmask_b32_e32 v25, v25, v26, vcc
	v_rsq_f32_e32 v25, v25
	s_nop 0
	v_mul_f32_e32 v26, 0x45800000, v25
	v_cndmask_b32_e32 v26, v25, v26, vcc
	v_mov_b32_e32 v25, 0
	s_and_saveexec_b64 s[0:1], s[40:41]
	s_cbranch_execz .LBB0_479
	v_mov_b32_e32 v25, v91
	v_mul_f32_e32 v27, v16, v26
	v_mul_f32_e32 v25, v27, v25

; DI float bf2f(unsigned h) { return __uint_as_float(h << 16); }
; DI float wave_sum(float v) {
; #pragma unroll
;   for (int o = 32; o >= 1; o >>= 1) v += __shfl_xor(v, o);
;   return v;
; DI void bpost_item(const Params& p, int l, int b, int item, bf16_t* lds) {
;     ...
;         float e0, e1;
;         if (qk == 0) { e0 = bf2f(YQ[(size_t)t * 384 + h * 96 + lane]) * rq; e1 = lane < 32 ? bf2f(YQ[(size_t)t * 384 + h * 96 + 64 + lane]) * rq : 0.f; }
;         else { e0 = bf2f(YKV[(size_t)t * 768 + h * 192 + lane]) * rkv; e1 = kr; }
;         float ss = wave_sum(e0 * e0 + e1 * e1);
;         const float r = rsqrtf(ss * (1.f / 96.f) + EPS);
;         const float* nw = (qk == 0 ? p.mqn : p.mkn) + l * 96;
;         float n0 = e0 * r * nw[lane];
;         float n1 = lane < 32 ? e1 * r * nw[64 + lane] : 0.f;
.LBB0_487:
	s_or_b64 exec, exec, s[0:1]
	v_mov_b32_e32 v17, v100
	v_lshlrev_b32_e32 v17, 16, v17
	v_mul_f32_e32 v17, v38, v17
	s_waitcnt lgkmcnt(0)
	v_fma_f32 v25, v17, v17, v24
	s_nop 1
	v_add_f32_dpp v25, v25, v25 quad_perm:[1,0,3,2] row_mask:0xf bank_mask:0xf
	s_nop 1
	v_add_f32_dpp v25, v25, v25 quad_perm:[2,3,0,1] row_mask:0xf bank_mask:0xf
	s_nop 1
	v_add_f32_dpp v25, v25, v25 row_half_mirror row_mask:0xf bank_mask:0xf
	s_nop 1
	v_add_f32_dpp v25, v25, v25 row_mirror row_mask:0xf bank_mask:0xf
	v_mov_b32_e32 v26, v25
	s_nop 1
	v_permlane16_swap_b32_e32 v25, v26
	s_nop 1
	v_add_f32_e32 v25, v25, v26
	v_mov_b32_e32 v26, v25
	s_nop 1
	v_permlane32_swap_b32_e32 v25, v26
	s_nop 1
	v_add_f32_e32 v25, v25, v26
	v_fmamk_f32 v25, v25, 0x3c2aaaab, v200
	v_mul_f32_e32 v26, 0x4b800000, v25
	v_cmp_gt_f32_e32 vcc, s58, v25
	s_nop 1
	v_cndmask_b32_e32 v25, v25, v26, vcc
	v_rsq_f32_e32 v25, v25
	s_nop 0
	v_mul_f32_e32 v26, 0x45800000, v25
	v_cndmask_b32_e32 v26, v25, v26, vcc
	v_mov_b32_e32 v25, 0
	s_and_saveexec_b64 s[0:1], s[40:41]
	s_cbranch_execz .LBB0_489
	v_mov_b32_e32 v25, v91
	v_mul_f32_e32 v27, v16, v26
	v_mul_f32_e32 v25, v27, v25

; DI float bf2f(unsigned h) { return __uint_as_float(h << 16); }
; DI float wave_sum(float v) {
; #pragma unroll
;   for (int o = 32; o >= 1; o >>= 1) v += __shfl_xor(v, o);
;   return v;
; DI void bpost_item(const Params& p, int l, int b, int item, bf16_t* lds) {
;     ...
;         float e0, e1;
;         if (qk == 0) { e0 = bf2f(YQ[(size_t)t * 384 + h * 96 + lane]) * rq; e1 = lane < 32 ? bf2f(YQ[(size_t)t * 384 + h * 96 + 64 + lane]) * rq : 0.f; }
;         else { e0 = bf2f(YKV[(size_t)t * 768 + h * 192 + lane]) * rkv; e1 = kr; }
;         float ss = wave_sum(e0 * e0 + e1 * e1);
;         const float r = rsqrtf(ss * (1.f / 96.f) + EPS);
;         const float* nw = (qk == 0 ? p.mqn : p.mkn) + l * 96;
;         float n0 = e0 * r * nw[lane];
;         float n1 = lane < 32 ? e1 * r * nw[64 + lane] : 0.f;
.LBB0_493:
	s_or_b64 exec, exec, s[0:1]
	s_waitcnt vmcnt(0)
	v_lshlrev_b32_e32 v20, 16, v25
	v_mul_f32_e32 v26, v39, v20
	v_pk_mul_f32 v[20:21], v[26:27], v[26:27]
	s_nop 0
	v_add_f32_e32 v20, v20, v21
	s_nop 1
	v_add_f32_dpp v20, v20, v20 quad_perm:[1,0,3,2] row_mask:0xf bank_mask:0xf
	s_nop 1
	v_add_f32_dpp v20, v20, v20 quad_perm:[2,3,0,1] row_mask:0xf bank_mask:0xf
	s_nop 1
	v_add_f32_dpp v20, v20, v20 row_half_mirror row_mask:0xf bank_mask:0xf
	s_nop 1
	v_add_f32_dpp v20, v20, v20 row_mirror row_mask:0xf bank_mask:0xf
	v_mov_b32_e32 v21, v20
	s_nop 1
	v_permlane16_swap_b32_e32 v20, v21
	s_nop 1
	v_add_f32_e32 v20, v20, v21
	v_mov_b32_e32 v21, v20
	s_nop 1
	v_permlane32_swap_b32_e32 v20, v21
	s_nop 1
	v_add_f32_e32 v20, v20, v21
	v_fmamk_f32 v20, v20, 0x3c2aaaab, v200
	v_mul_f32_e32 v21, 0x4b800000, v20
	v_cmp_gt_f32_e32 vcc, s58, v20
	s_nop 1
	v_cndmask_b32_e32 v20, v20, v21, vcc
	v_rsq_f32_e32 v20, v20
	s_nop 0
	v_mul_f32_e32 v21, 0x45800000, v20
	v_cndmask_b32_e32 v20, v20, v21, vcc
	s_and_saveexec_b64 s[0:1], s[40:41]
	s_cbranch_execz .LBB0_495
	v_mov_b32_e32 v17, v90
	v_mul_f32_e32 v21, v27, v20
	v_mul_f32_e32 v17, v21, v17

; DI int otid() { int t = (int)__builtin_amdgcn_workitem_id_x(); asm volatile("" : "+v"(t)); return t; }
; DI bf16_t f2bf(float f) { return (bf16_t)(pk2(f, 0.f) & 0xffffu); }
; DI float bflo(unsigned u) { return __uint_as_float(u << 16); }
; DI float bfhi(unsigned u) { return __uint_as_float(u & 0xffff0000u); }
; DI void vt_transpose(const bf16_t* src, int ld, const float* srs, bf16_t* dstVt, int t0, bf16_t* sT) {
;   const int tid = otid();
;   __syncthreads();
;   {
;     const int row = tid >> 4, col8 = (tid & 15) * 8;
;     u32x4 v = *(const u32x4*)(src + (size_t)row * ld + col8);
;     const float sc = srs ? srs[row] : 1.f;
;     unsigned w[4] = {v.x, v.y, v.z, v.w};
; #pragma unroll
;     for (int j = 0; j < 4; ++j) { sT[row * 130 + col8 + 2 * j] = f2bf(bflo(w[j]) * sc); sT[row * 130 + col8 + 2 * j + 1] = f2bf(bfhi(w[j]) * sc); }
;   }
;   __syncthreads();
;   const int p16 = tid & 15, half = p16 >> 3, jj = p16 & 7, dg = tid >> 4;
;   const int key = (jj >> 2) * 8 + half * 4 + (jj & 3);
; #pragma unroll
;   for (int i = 0; i < 8; ++i) { const int d = dg * 8 + i; dstVt[(size_t)d * TT + t0 + p16] = sT[key * 130 + d]; }
; }
; DI void bpost_item(const Params& p, int l, int b, int item, bf16_t* lds) {
;     ...
;   for (int h = 0; h < 4; ++h)
;     vt_transpose(YKV + (size_t)t0 * 768 + h * 192 + 64, 768, srs, (bf16_t*)(p.ws + OFF_VTB) + (size_t)h * 128 * TT, t0, lds);
.LBB0_503:
	v_lshlrev_b32_e32 v10, 3, v8
	v_mul_lo_u32 v11, v7, s12
	v_lshl_add_u32 v10, v10, 1, v11
	s_waitcnt vmcnt(0)
	v_lshlrev_b32_e32 v11, 16, v2
	v_and_b32_e32 v2, 0xffff0000, v2
	v_lshlrev_b32_e32 v12, 16, v3
	v_and_b32_e32 v3, 0xffff0000, v3
	s_waitcnt lgkmcnt(0)
	v_mul_f32_e32 v11, v0, v11
	v_mul_f32_e32 v2, v0, v2
	v_mul_f32_e32 v12, v0, v12
	v_mul_f32_e32 v3, v0, v3
	v_cvt_pk_bf16_f32 v3, v12, v3
	v_cvt_pk_bf16_f32 v2, v11, v2
	ds_write2_b32 v10, v2, v3 offset1:1
	v_lshlrev_b32_e32 v2, 16, v4
	v_and_b32_e32 v3, 0xffff0000, v4
	v_lshlrev_b32_e32 v4, 16, v5
	v_and_b32_e32 v5, 0xffff0000, v5
	v_mul_f32_e32 v2, v0, v2
	v_mul_f32_e32 v3, v0, v3
	v_mul_f32_e32 v4, v0, v4
	v_mul_f32_e32 v0, v0, v5
	v_cvt_pk_bf16_f32 v0, v4, v0
	v_cvt_pk_bf16_f32 v2, v2, v3
	ds_write2_b32 v10, v2, v0 offset0:2 offset1:3
	v_lshlrev_b32_e32 v0, 1, v9
	v_lshrrev_b32_e32 v2, 1, v9
	s_lshl_b32 s5, s4, 5
	v_and_b32_e32 v0, 8, v0
	v_and_b32_e32 v2, 4, v2
	v_and_b32_e32 v3, 3, v9
	s_add_u32 s6, s28, s5
	v_or3_b32 v3, v0, v2, v3
	s_addc_u32 s7, s29, 0
	v_lshlrev_b32_e32 v0, 1, v8
	v_lshl_add_u64 v[4:5], s[6:7], 0, v[0:1]
	v_lshlrev_b32_e32 v0, 4, v7
	v_mad_u32_u24 v0, v3, s12, v0
	s_waitcnt lgkmcnt(0)
	s_barrier
	v_and_b32_e32 v144, 0x7f, v201
	v_lshrrev_b32_e32 v145, 7, v201
	v_mul_u32_u24_e32 v146, 0x410, v145
	v_lshl_add_u32 v146, v144, 1, v146
	ds_read_u16 v148, v146 offset:0
	ds_read_u16 v149, v146 offset:260
	ds_read_u16 v150, v146 offset:520
	ds_read_u16 v151, v146 offset:780
	ds_read_u16 v152, v146 offset:2080
	ds_read_u16 v153, v146 offset:2340
	ds_read_u16 v154, v146 offset:2600
	ds_read_u16 v155, v146 offset:2860
	v_lshlrev_b32_e32 v147, 15, v144
	v_lshl_add_u32 v147, v145, 4, v147
	s_waitcnt lgkmcnt(0)
	v_lshl_or_b32 v156, v149, 16, v148
	v_lshl_or_b32 v157, v151, 16, v150
	v_lshl_or_b32 v158, v153, 16, v152
	v_lshl_or_b32 v159, v155, 16, v154
	global_store_dwordx4 v147, v[156:159], s[6:7]
	v_mov_b32_e32 v9, v201
	v_mov_b64_e32 v[2:3], s[0:1]
	v_ashrrev_i32_e32 v7, 4, v9
	v_and_b32_e32 v8, 15, v9
	s_movk_i32 s5, 0x600
	v_mad_i64_i32 v[2:3], s[6:7], v7, s5, v[2:3]
	v_lshlrev_b32_e32 v0, 4, v8
	v_lshl_add_u64 v[2:3], v[2:3], 0, v[0:1]
	s_barrier
	global_load_dwordx4 v[2:5], v[2:3], off offset:512
	s_mov_b64 s[6:7], -1
	v_cndmask_b32_e64 v0, 0, 1, s[6:7]
	v_cmp_ne_u32_e64 s[38:39], 1, v0
	v_lshlrev_b32_e32 v0, 2, v7
	ds_read_b32 v6, v0 offset:16640
	v_lshlrev_b32_e32 v0, 3, v8
	v_mul_lo_u32 v10, v7, s12
	v_lshl_add_u32 v0, v0, 1, v10
	s_waitcnt vmcnt(0)
	v_lshlrev_b32_e32 v10, 16, v2
	v_and_b32_e32 v2, 0xffff0000, v2
	v_lshlrev_b32_e32 v11, 16, v3
	v_and_b32_e32 v3, 0xffff0000, v3
	s_waitcnt lgkmcnt(0)
	v_mul_f32_e32 v10, v6, v10
	v_mul_f32_e32 v2, v6, v2
	v_mul_f32_e32 v11, v6, v11
	v_mul_f32_e32 v3, v6, v3
	v_cvt_pk_bf16_f32 v3, v11, v3
	v_cvt_pk_bf16_f32 v2, v10, v2
	ds_write2_b32 v0, v2, v3 offset1:1
	v_lshlrev_b32_e32 v2, 16, v4
	v_and_b32_e32 v3, 0xffff0000, v4
	v_lshlrev_b32_e32 v4, 16, v5
	v_and_b32_e32 v5, 0xffff0000, v5
	v_mul_f32_e32 v2, v6, v2
	v_mul_f32_e32 v3, v6, v3
	v_mul_f32_e32 v4, v6, v4
	v_mul_f32_e32 v5, v6, v5
	s_lshl_b32 s4, s4, 4
	v_cvt_pk_bf16_f32 v4, v4, v5
	v_cvt_pk_bf16_f32 v2, v2, v3
	ds_write2_b32 v0, v2, v4 offset0:2 offset1:3
	v_lshlrev_b32_e32 v0, 1, v9
	v_lshrrev_b32_e32 v2, 1, v9
	s_lshl_b32 s4, s4, 1
	v_and_b32_e32 v0, 8, v0
	v_and_b32_e32 v2, 4, v2
	v_and_b32_e32 v3, 3, v9
	s_add_u32 s6, s30, s4
	v_or3_b32 v3, v0, v2, v3
	s_addc_u32 s7, s31, 0
	v_lshlrev_b32_e32 v0, 1, v8
	v_lshl_add_u64 v[4:5], s[6:7], 0, v[0:1]
	v_lshlrev_b32_e32 v0, 4, v7
	v_mad_u32_u24 v0, v3, s12, v0
	s_waitcnt lgkmcnt(0)
	s_barrier
	v_and_b32_e32 v144, 0x7f, v201
	v_lshrrev_b32_e32 v145, 7, v201
	v_mul_u32_u24_e32 v146, 0x410, v145
	v_lshl_add_u32 v146, v144, 1, v146
	ds_read_u16 v148, v146 offset:0
	ds_read_u16 v149, v146 offset:260
	ds_read_u16 v150, v146 offset:520
	ds_read_u16 v151, v146 offset:780
	ds_read_u16 v152, v146 offset:2080
	ds_read_u16 v153, v146 offset:2340
	ds_read_u16 v154, v146 offset:2600
	ds_read_u16 v155, v146 offset:2860
	v_lshlrev_b32_e32 v147, 15, v144
	v_lshl_add_u32 v147, v145, 4, v147
	s_waitcnt lgkmcnt(0)
	v_lshl_or_b32 v156, v149, 16, v148
	v_lshl_or_b32 v157, v151, 16, v150
	v_lshl_or_b32 v158, v153, 16, v152
	v_lshl_or_b32 v159, v155, 16, v154
	global_store_dwordx4 v147, v[156:159], s[6:7]
	s_and_b64 vcc, exec, s[38:39]
	v_mov_b32_e32 v9, v201
	v_mov_b64_e32 v[2:3], s[0:1]
	v_ashrrev_i32_e32 v7, 4, v9
	v_and_b32_e32 v8, 15, v9
	v_mad_i64_i32 v[2:3], s[6:7], v7, s5, v[2:3]
	v_lshlrev_b32_e32 v0, 4, v8
	v_lshl_add_u64 v[2:3], v[2:3], 0, v[0:1]
	s_barrier
	global_load_dwordx4 v[2:5], v[2:3], off offset:896
	v_mov_b32_e32 v6, 1.0
	v_mov_b32_e32 v0, 1.0
	s_cbranch_vccnz .LBB0_507
	v_lshlrev_b32_e32 v0, 2, v7
	ds_read_b32 v0, v0 offset:16640
; DI int otid() { int t = (int)__builtin_amdgcn_workitem_id_x(); asm volatile("" : "+v"(t)); return t; }
; DI bf16_t f2bf(float f) { return (bf16_t)(pk2(f, 0.f) & 0xffffu); }
; DI float bflo(unsigned u) { return __uint_as_float(u << 16); }
; DI float bfhi(unsigned u) { return __uint_as_float(u & 0xffff0000u); }
; DI void vt_transpose(const bf16_t* src, int ld, const float* srs, bf16_t* dstVt, int t0, bf16_t* sT) {
;   const int tid = otid();
;   __syncthreads();
;   {
;     const int row = tid >> 4, col8 = (tid & 15) * 8;
;     u32x4 v = *(const u32x4*)(src + (size_t)row * ld + col8);
;     const float sc = srs ? srs[row] : 1.f;
;     unsigned w[4] = {v.x, v.y, v.z, v.w};
; #pragma unroll
;     for (int j = 0; j < 4; ++j) { sT[row * 130 + col8 + 2 * j] = f2bf(bflo(w[j]) * sc); sT[row * 130 + col8 + 2 * j + 1] = f2bf(bfhi(w[j]) * sc); }
;   }
;   __syncthreads();
;   const int p16 = tid & 15, half = p16 >> 3, jj = p16 & 7, dg = tid >> 4;
;   const int key = (jj >> 2) * 8 + half * 4 + (jj & 3);
; #pragma unroll
;   for (int i = 0; i < 8; ++i) { const int d = dg * 8 + i; dstVt[(size_t)d * TT + t0 + p16] = sT[key * 130 + d]; }
; }
; DI void bpost_item(const Params& p, int l, int b, int item, bf16_t* lds) {
;     ...
;   for (int h = 0; h < 4; ++h)
;     vt_transpose(YKV + (size_t)t0 * 768 + h * 192 + 64, 768, srs, (bf16_t*)(p.ws + OFF_VTB) + (size_t)h * 128 * TT, t0, lds);
.LBB0_507:
	v_lshlrev_b32_e32 v10, 3, v8
	v_mul_lo_u32 v11, v7, s12
	v_lshl_add_u32 v10, v10, 1, v11
	s_waitcnt vmcnt(0)
	v_lshlrev_b32_e32 v11, 16, v2
	v_and_b32_e32 v2, 0xffff0000, v2
	v_lshlrev_b32_e32 v12, 16, v3
	v_and_b32_e32 v3, 0xffff0000, v3
	s_waitcnt lgkmcnt(0)
	v_mul_f32_e32 v11, v0, v11
	v_mul_f32_e32 v2, v0, v2
	v_mul_f32_e32 v12, v0, v12
	v_mul_f32_e32 v3, v0, v3
	v_cvt_pk_bf16_f32 v3, v12, v3
	v_cvt_pk_bf16_f32 v2, v11, v2
	ds_write2_b32 v10, v2, v3 offset1:1
	v_lshlrev_b32_e32 v2, 16, v4
	v_and_b32_e32 v3, 0xffff0000, v4
	v_lshlrev_b32_e32 v4, 16, v5
	v_and_b32_e32 v5, 0xffff0000, v5
	v_mul_f32_e32 v2, v0, v2
	v_mul_f32_e32 v3, v0, v3
	v_mul_f32_e32 v4, v0, v4
	v_mul_f32_e32 v0, v0, v5
	v_cvt_pk_bf16_f32 v0, v4, v0
	v_cvt_pk_bf16_f32 v2, v2, v3
	ds_write2_b32 v10, v2, v0 offset0:2 offset1:3
	v_lshlrev_b32_e32 v0, 1, v9
	v_lshrrev_b32_e32 v2, 1, v9
	v_and_b32_e32 v0, 8, v0
	v_and_b32_e32 v2, 4, v2
	v_and_b32_e32 v3, 3, v9
	s_add_u32 s6, s36, s4
	v_or3_b32 v3, v0, v2, v3
	s_addc_u32 s7, s37, 0
	v_lshlrev_b32_e32 v0, 1, v8
	v_lshl_add_u64 v[4:5], s[6:7], 0, v[0:1]
	v_lshlrev_b32_e32 v0, 4, v7
	v_mad_u32_u24 v0, v3, s12, v0
	s_waitcnt lgkmcnt(0)
	s_barrier
	v_and_b32_e32 v144, 0x7f, v201
	v_lshrrev_b32_e32 v145, 7, v201
	v_mul_u32_u24_e32 v146, 0x410, v145
	v_lshl_add_u32 v146, v144, 1, v146
	ds_read_u16 v148, v146 offset:0
	ds_read_u16 v149, v146 offset:260
	ds_read_u16 v150, v146 offset:520
	ds_read_u16 v151, v146 offset:780
	ds_read_u16 v152, v146 offset:2080
	ds_read_u16 v153, v146 offset:2340
	ds_read_u16 v154, v146 offset:2600
	ds_read_u16 v155, v146 offset:2860
	v_lshlrev_b32_e32 v147, 15, v144
	v_lshl_add_u32 v147, v145, 4, v147
	s_waitcnt lgkmcnt(0)
	v_lshl_or_b32 v156, v149, 16, v148
	v_lshl_or_b32 v157, v151, 16, v150
	v_lshl_or_b32 v158, v153, 16, v152
	v_lshl_or_b32 v159, v155, 16, v154
	global_store_dwordx4 v147, v[156:159], s[6:7]
	v_mov_b32_e32 v9, v201
	v_mov_b64_e32 v[2:3], s[0:1]
	v_ashrrev_i32_e32 v7, 4, v9
	v_and_b32_e32 v8, 15, v9
	s_movk_i32 s0, 0x600
	v_mad_i64_i32 v[2:3], s[0:1], v7, s0, v[2:3]
	v_lshlrev_b32_e32 v0, 4, v8
	v_lshl_add_u64 v[2:3], v[2:3], 0, v[0:1]
	s_barrier
	global_load_dwordx4 v[2:5], v[2:3], off offset:1280
	s_and_b64 vcc, exec, s[38:39]
	s_cbranch_vccnz .LBB0_509
	v_lshlrev_b32_e32 v0, 2, v7
	ds_read_b32 v6, v0 offset:16640
.LBB0_509:
	v_lshlrev_b32_e32 v0, 3, v8
	v_mul_lo_u32 v10, v7, s12
	v_lshl_add_u32 v0, v0, 1, v10
	s_waitcnt vmcnt(0)
	v_lshlrev_b32_e32 v10, 16, v2
	v_and_b32_e32 v2, 0xffff0000, v2
	v_lshlrev_b32_e32 v11, 16, v3
	v_and_b32_e32 v3, 0xffff0000, v3
	s_waitcnt lgkmcnt(0)
	v_mul_f32_e32 v10, v6, v10
	v_mul_f32_e32 v2, v6, v2
	v_mul_f32_e32 v11, v6, v11
	v_mul_f32_e32 v3, v6, v3
	v_cvt_pk_bf16_f32 v3, v11, v3
	v_cvt_pk_bf16_f32 v2, v10, v2
	ds_write2_b32 v0, v2, v3 offset1:1
	v_lshlrev_b32_e32 v2, 16, v4
	v_and_b32_e32 v3, 0xffff0000, v4
	v_lshlrev_b32_e32 v4, 16, v5
	v_and_b32_e32 v5, 0xffff0000, v5
	v_mul_f32_e32 v2, v6, v2
	v_mul_f32_e32 v3, v6, v3
	v_mul_f32_e32 v4, v6, v4
	v_mul_f32_e32 v5, v6, v5
	v_cvt_pk_bf16_f32 v4, v4, v5
	v_cvt_pk_bf16_f32 v2, v2, v3
	ds_write2_b32 v0, v2, v4 offset0:2 offset1:3
	v_lshlrev_b32_e32 v0, 1, v9
	v_lshrrev_b32_e32 v2, 1, v9
	v_and_b32_e32 v0, 8, v0
	v_and_b32_e32 v2, 4, v2
	v_and_b32_e32 v3, 3, v9
	s_add_u32 s0, s62, s4
	v_or3_b32 v3, v0, v2, v3
	s_addc_u32 s1, s63, 0
	v_lshlrev_b32_e32 v0, 1, v8
	v_lshl_add_u64 v[4:5], s[0:1], 0, v[0:1]
	v_lshlrev_b32_e32 v0, 4, v7
	v_mad_u32_u24 v0, v3, s12, v0
	s_waitcnt lgkmcnt(0)
	s_barrier
	v_and_b32_e32 v144, 0x7f, v201
	v_lshrrev_b32_e32 v145, 7, v201
	v_mul_u32_u24_e32 v146, 0x410, v145
	v_lshl_add_u32 v146, v144, 1, v146
	ds_read_u16 v148, v146 offset:0
	ds_read_u16 v149, v146 offset:260
	ds_read_u16 v150, v146 offset:520
	ds_read_u16 v151, v146 offset:780
	ds_read_u16 v152, v146 offset:2080
	ds_read_u16 v153, v146 offset:2340
	ds_read_u16 v154, v146 offset:2600
	ds_read_u16 v155, v146 offset:2860
	v_lshlrev_b32_e32 v147, 15, v144
	v_lshl_add_u32 v147, v145, 4, v147
	s_waitcnt lgkmcnt(0)
	v_lshl_or_b32 v156, v149, 16, v148
	v_lshl_or_b32 v157, v151, 16, v150
	v_lshl_or_b32 v158, v153, 16, v152
	v_lshl_or_b32 v159, v155, 16, v154
	global_store_dwordx4 v147, v[156:159], s[0:1]
	s_mov_b64 s[0:1], 0
	s_barrier

; DI int otid() { int t = (int)__builtin_amdgcn_workitem_id_x(); asm volatile("" : "+v"(t)); return t; }
; DI bf16_t f2bf(float f) { return (bf16_t)(pk2(f, 0.f) & 0xffffu); }
; DI float bflo(unsigned u) { return __uint_as_float(u << 16); }
; DI float bfhi(unsigned u) { return __uint_as_float(u & 0xffff0000u); }
; DI void vt_transpose(const bf16_t* src, int ld, const float* srs, bf16_t* dstVt, int t0, bf16_t* sT) {
;   const int tid = otid();
;   __syncthreads();
;   {
;     const int row = tid >> 4, col8 = (tid & 15) * 8;
;     u32x4 v = *(const u32x4*)(src + (size_t)row * ld + col8);
;     const float sc = srs ? srs[row] : 1.f;
;     unsigned w[4] = {v.x, v.y, v.z, v.w};
; #pragma unroll
;     for (int j = 0; j < 4; ++j) { sT[row * 130 + col8 + 2 * j] = f2bf(bflo(w[j]) * sc); sT[row * 130 + col8 + 2 * j + 1] = f2bf(bfhi(w[j]) * sc); }
;   }
;   __syncthreads();
;   const int p16 = tid & 15, half = p16 >> 3, jj = p16 & 7, dg = tid >> 4;
;   const int key = (jj >> 2) * 8 + half * 4 + (jj & 3);
; #pragma unroll
;   for (int i = 0; i < 8; ++i) { const int d = dg * 8 + i; dstVt[(size_t)d * TT + t0 + p16] = sT[key * 130 + d]; }
; }
; DI void prep_ew_item(const Params& p, int l, int item, bf16_t* lds) {
;     ...
;   for (int h = 0; h < 4; ++h)
;     vt_transpose(RA + (size_t)t0 * 1536 + 1024 + h * 128, 1536, nullptr, (bf16_t*)(p.ws + OFF_VTA) + (size_t)h * 128 * TT, t0, lds);
.LBB0_907:
	s_add_i32 s6, s89, 0xfffffb80
	s_mul_i32 s34, s6, 0x6000
	s_lshl_b64 s[4:5], s[34:35], 1
	s_add_u32 s4, s94, s4
	s_addc_u32 s5, s95, s5
	v_mov_b32_e32 v10, v201
	v_mov_b64_e32 v[2:3], s[4:5]
	v_ashrrev_i32_e32 v11, 4, v10
	v_and_b32_e32 v12, 15, v10
	v_mad_i64_i32 v[4:5], s[4:5], v11, s57, v[2:3]
	v_lshlrev_b32_e32 v0, 4, v12
	v_lshl_add_u64 v[4:5], v[4:5], 0, v[0:1]
	s_mov_b32 s8, 0x6c00000
	v_add_co_u32_e32 v4, vcc, s8, v4
	s_nop 1
	v_addc_co_u32_e32 v5, vcc, 0, v5, vcc
	s_barrier
	global_load_dwordx4 v[4:7], v[4:5], off offset:2048
	v_mad_u64_u32 v[8:9], s[4:5], v11, s10, v[0:1]
	s_lshl_b32 s4, s6, 5
	s_add_u32 s6, s31, s4
	s_addc_u32 s7, s36, 0
	s_mov_b64 s[26:27], 0
	s_mov_b32 s33, 0xfffffc0
	s_waitcnt vmcnt(0)
	v_lshlrev_b32_e32 v0, 16, v4
	v_and_b32_e32 v4, 0xffff0000, v4
	v_lshlrev_b32_e32 v9, 16, v5
	v_and_b32_e32 v5, 0xffff0000, v5
	v_cvt_pk_bf16_f32 v5, v9, v5
	v_cvt_pk_bf16_f32 v0, v0, v4
	ds_write2_b32 v8, v0, v5 offset1:1
	v_lshlrev_b32_e32 v0, 16, v6
	v_and_b32_e32 v4, 0xffff0000, v6
	v_lshlrev_b32_e32 v5, 16, v7
	v_and_b32_e32 v6, 0xffff0000, v7
	v_cvt_pk_bf16_f32 v5, v5, v6
	v_cvt_pk_bf16_f32 v0, v0, v4
	ds_write2_b32 v8, v0, v5 offset0:2 offset1:3
	v_lshlrev_b32_e32 v0, 1, v10
	v_lshrrev_b32_e32 v4, 1, v10
	v_and_b32_e32 v0, 8, v0
	v_and_b32_e32 v4, 4, v4
	v_and_b32_e32 v5, 3, v10
	v_or3_b32 v5, v0, v4, v5
	v_lshlrev_b32_e32 v0, 1, v12
	v_lshl_add_u64 v[6:7], s[6:7], 0, v[0:1]
	v_and_b32_e32 v0, -16, v10
	v_mad_u32_u24 v0, v5, s10, v0
	s_waitcnt lgkmcnt(0)
	s_barrier
	v_and_b32_e32 v144, 0x7f, v201
	v_lshrrev_b32_e32 v145, 7, v201
	v_mul_u32_u24_e32 v146, 0x410, v145
	v_lshl_add_u32 v146, v144, 1, v146
	ds_read_u16 v148, v146 offset:0
	ds_read_u16 v149, v146 offset:260
	ds_read_u16 v150, v146 offset:520
	ds_read_u16 v151, v146 offset:780
	ds_read_u16 v152, v146 offset:2080
	ds_read_u16 v153, v146 offset:2340
	ds_read_u16 v154, v146 offset:2600
	ds_read_u16 v155, v146 offset:2860
	v_lshlrev_b32_e32 v147, 15, v144
	v_lshl_add_u32 v147, v145, 4, v147
	s_waitcnt lgkmcnt(0)
	v_lshl_or_b32 v156, v149, 16, v148
	v_lshl_or_b32 v157, v151, 16, v150
	v_lshl_or_b32 v158, v153, 16, v152
	v_lshl_or_b32 v159, v155, 16, v154
	global_store_dwordx4 v147, v[156:159], s[6:7]
	v_mov_b32_e32 v10, v201
	s_nop 0
	v_ashrrev_i32_e32 v11, 4, v10
	v_and_b32_e32 v12, 15, v10
	v_mad_i64_i32 v[4:5], s[6:7], v11, s57, v[2:3]
	v_lshlrev_b32_e32 v0, 4, v12
	v_lshl_add_u64 v[4:5], v[4:5], 0, v[0:1]
	v_add_co_u32_e32 v4, vcc, s8, v4
	s_barrier
	s_nop 0
	v_addc_co_u32_e32 v5, vcc, 0, v5, vcc
	global_load_dwordx4 v[4:7], v[4:5], off offset:2304
	v_mad_u64_u32 v[8:9], s[6:7], v11, s10, v[0:1]
	s_add_u32 s6, s37, s4
	s_addc_u32 s7, s14, 0
	s_waitcnt vmcnt(0)
	v_lshlrev_b32_e32 v0, 16, v4
	v_and_b32_e32 v4, 0xffff0000, v4
	v_lshlrev_b32_e32 v9, 16, v5
	v_and_b32_e32 v5, 0xffff0000, v5
	v_cvt_pk_bf16_f32 v5, v9, v5
	v_cvt_pk_bf16_f32 v0, v0, v4
	ds_write2_b32 v8, v0, v5 offset1:1
	v_lshlrev_b32_e32 v0, 16, v6
	v_and_b32_e32 v4, 0xffff0000, v6
	v_lshlrev_b32_e32 v5, 16, v7
	v_and_b32_e32 v6, 0xffff0000, v7
	v_cvt_pk_bf16_f32 v5, v5, v6
	v_cvt_pk_bf16_f32 v0, v0, v4
	ds_write2_b32 v8, v0, v5 offset0:2 offset1:3
	v_lshlrev_b32_e32 v0, 1, v10
	v_lshrrev_b32_e32 v4, 1, v10
	v_and_b32_e32 v0, 8, v0
	v_and_b32_e32 v4, 4, v4
	v_and_b32_e32 v5, 3, v10
	v_or3_b32 v5, v0, v4, v5
	v_lshlrev_b32_e32 v0, 1, v12
	v_lshl_add_u64 v[6:7], s[6:7], 0, v[0:1]
	v_and_b32_e32 v0, -16, v10
	v_mad_u32_u24 v0, v5, s10, v0
	s_waitcnt lgkmcnt(0)
	s_barrier
	v_and_b32_e32 v144, 0x7f, v201
	v_lshrrev_b32_e32 v145, 7, v201
	v_mul_u32_u24_e32 v146, 0x410, v145
	v_lshl_add_u32 v146, v144, 1, v146
	ds_read_u16 v148, v146 offset:0
	ds_read_u16 v149, v146 offset:260
	ds_read_u16 v150, v146 offset:520
	ds_read_u16 v151, v146 offset:780
	ds_read_u16 v152, v146 offset:2080
	ds_read_u16 v153, v146 offset:2340
	ds_read_u16 v154, v146 offset:2600
	ds_read_u16 v155, v146 offset:2860
	v_lshlrev_b32_e32 v147, 15, v144
	v_lshl_add_u32 v147, v145, 4, v147
	s_waitcnt lgkmcnt(0)
	v_lshl_or_b32 v156, v149, 16, v148
	v_lshl_or_b32 v157, v151, 16, v150
	v_lshl_or_b32 v158, v153, 16, v152
	v_lshl_or_b32 v159, v155, 16, v154
	global_store_dwordx4 v147, v[156:159], s[6:7]
	v_mov_b32_e32 v10, v201
	s_nop 0
	v_ashrrev_i32_e32 v11, 4, v10
	v_and_b32_e32 v12, 15, v10
	v_mad_i64_i32 v[4:5], s[6:7], v11, s57, v[2:3]
	v_lshlrev_b32_e32 v0, 4, v12
	v_lshl_add_u64 v[4:5], v[4:5], 0, v[0:1]
	v_add_co_u32_e32 v4, vcc, s8, v4
	s_barrier
; DI int otid() { int t = (int)__builtin_amdgcn_workitem_id_x(); asm volatile("" : "+v"(t)); return t; }
; DI bf16_t f2bf(float f) { return (bf16_t)(pk2(f, 0.f) & 0xffffu); }
; DI float bflo(unsigned u) { return __uint_as_float(u << 16); }
; DI float bfhi(unsigned u) { return __uint_as_float(u & 0xffff0000u); }
; DI void vt_transpose(const bf16_t* src, int ld, const float* srs, bf16_t* dstVt, int t0, bf16_t* sT) {
;   const int tid = otid();
;   __syncthreads();
;   {
;     const int row = tid >> 4, col8 = (tid & 15) * 8;
;     u32x4 v = *(const u32x4*)(src + (size_t)row * ld + col8);
;     const float sc = srs ? srs[row] : 1.f;
;     unsigned w[4] = {v.x, v.y, v.z, v.w};
; #pragma unroll
;     for (int j = 0; j < 4; ++j) { sT[row * 130 + col8 + 2 * j] = f2bf(bflo(w[j]) * sc); sT[row * 130 + col8 + 2 * j + 1] = f2bf(bfhi(w[j]) * sc); }
;   }
;   __syncthreads();
;   const int p16 = tid & 15, half = p16 >> 3, jj = p16 & 7, dg = tid >> 4;
;   const int key = (jj >> 2) * 8 + half * 4 + (jj & 3);
; #pragma unroll
;   for (int i = 0; i < 8; ++i) { const int d = dg * 8 + i; dstVt[(size_t)d * TT + t0 + p16] = sT[key * 130 + d]; }
; }
; DI void prep_ew_item(const Params& p, int l, int item, bf16_t* lds) {
;     ...
;   for (int h = 0; h < 4; ++h)
;     vt_transpose(RA + (size_t)t0 * 1536 + 1024 + h * 128, 1536, nullptr, (bf16_t*)(p.ws + OFF_VTA) + (size_t)h * 128 * TT, t0, lds);
	s_nop 0
	v_addc_co_u32_e32 v5, vcc, 0, v5, vcc
	global_load_dwordx4 v[4:7], v[4:5], off offset:2560
	v_mad_u64_u32 v[8:9], s[6:7], v11, s10, v[0:1]
	s_add_u32 s6, s15, s4
	s_addc_u32 s7, s16, 0
	s_add_u32 s4, s17, s4
	s_addc_u32 s5, s18, 0
	s_waitcnt vmcnt(0)
	v_lshlrev_b32_e32 v0, 16, v4
	v_and_b32_e32 v4, 0xffff0000, v4
	v_lshlrev_b32_e32 v9, 16, v5
	v_and_b32_e32 v5, 0xffff0000, v5
	v_cvt_pk_bf16_f32 v5, v9, v5
	v_cvt_pk_bf16_f32 v0, v0, v4
	ds_write2_b32 v8, v0, v5 offset1:1
	v_lshlrev_b32_e32 v0, 16, v6
	v_and_b32_e32 v4, 0xffff0000, v6
	v_lshlrev_b32_e32 v5, 16, v7
	v_and_b32_e32 v6, 0xffff0000, v7
	v_cvt_pk_bf16_f32 v5, v5, v6
	v_cvt_pk_bf16_f32 v0, v0, v4
	ds_write2_b32 v8, v0, v5 offset0:2 offset1:3
	v_lshlrev_b32_e32 v0, 1, v10
	v_lshrrev_b32_e32 v4, 1, v10
	v_and_b32_e32 v0, 8, v0
	v_and_b32_e32 v4, 4, v4
	v_and_b32_e32 v5, 3, v10
	v_or3_b32 v5, v0, v4, v5
	v_lshlrev_b32_e32 v0, 1, v12
	v_lshl_add_u64 v[6:7], s[6:7], 0, v[0:1]
	v_and_b32_e32 v0, -16, v10
	v_mad_u32_u24 v0, v5, s10, v0
	s_waitcnt lgkmcnt(0)
	s_barrier
	v_and_b32_e32 v144, 0x7f, v201
	v_lshrrev_b32_e32 v145, 7, v201
	v_mul_u32_u24_e32 v146, 0x410, v145
	v_lshl_add_u32 v146, v144, 1, v146
	ds_read_u16 v148, v146 offset:0
	ds_read_u16 v149, v146 offset:260
	ds_read_u16 v150, v146 offset:520
	ds_read_u16 v151, v146 offset:780
	ds_read_u16 v152, v146 offset:2080
	ds_read_u16 v153, v146 offset:2340
	ds_read_u16 v154, v146 offset:2600
	ds_read_u16 v155, v146 offset:2860
	v_lshlrev_b32_e32 v147, 15, v144
	v_lshl_add_u32 v147, v145, 4, v147
	s_waitcnt lgkmcnt(0)
	v_lshl_or_b32 v156, v149, 16, v148
	v_lshl_or_b32 v157, v151, 16, v150
	v_lshl_or_b32 v158, v153, 16, v152
	v_lshl_or_b32 v159, v155, 16, v154
	global_store_dwordx4 v147, v[156:159], s[6:7]
	v_mov_b32_e32 v8, v201
	s_nop 0
	v_ashrrev_i32_e32 v9, 4, v8
	v_and_b32_e32 v10, 15, v8
	v_mad_i64_i32 v[2:3], s[6:7], v9, s57, v[2:3]
	v_lshlrev_b32_e32 v0, 4, v10
	v_lshl_add_u64 v[2:3], v[2:3], 0, v[0:1]
	v_add_co_u32_e32 v2, vcc, s8, v2
	s_barrier
	s_nop 0
	v_addc_co_u32_e32 v3, vcc, 0, v3, vcc
	global_load_dwordx4 v[2:5], v[2:3], off offset:2816
	v_mad_u64_u32 v[6:7], s[6:7], v9, s10, v[0:1]
	s_waitcnt vmcnt(0)
	v_lshlrev_b32_e32 v0, 16, v2
	v_and_b32_e32 v2, 0xffff0000, v2
	v_lshlrev_b32_e32 v7, 16, v3
	v_and_b32_e32 v3, 0xffff0000, v3
	v_cvt_pk_bf16_f32 v3, v7, v3
	v_cvt_pk_bf16_f32 v0, v0, v2
	ds_write2_b32 v6, v0, v3 offset1:1
	v_lshlrev_b32_e32 v0, 16, v4
	v_and_b32_e32 v2, 0xffff0000, v4
	v_lshlrev_b32_e32 v3, 16, v5
	v_and_b32_e32 v4, 0xffff0000, v5
	v_cvt_pk_bf16_f32 v3, v3, v4
	v_cvt_pk_bf16_f32 v0, v0, v2
	ds_write2_b32 v6, v0, v3 offset0:2 offset1:3
	v_lshlrev_b32_e32 v0, 1, v8
	v_lshrrev_b32_e32 v2, 1, v8
	v_and_b32_e32 v0, 8, v0
	v_and_b32_e32 v2, 4, v2
	v_and_b32_e32 v3, 3, v8
	v_or3_b32 v5, v0, v2, v3
	v_lshlrev_b32_e32 v0, 1, v10
	v_lshl_add_u64 v[2:3], s[4:5], 0, v[0:1]
	v_and_b32_e32 v0, -16, v8
	v_mad_u32_u24 v0, v5, s10, v0
	s_waitcnt lgkmcnt(0)
	s_barrier
	v_and_b32_e32 v144, 0x7f, v201
	v_lshrrev_b32_e32 v145, 7, v201
	v_mul_u32_u24_e32 v146, 0x410, v145
	v_lshl_add_u32 v146, v144, 1, v146
	ds_read_u16 v148, v146 offset:0
	ds_read_u16 v149, v146 offset:260
	ds_read_u16 v150, v146 offset:520
	ds_read_u16 v151, v146 offset:780
	ds_read_u16 v152, v146 offset:2080
	ds_read_u16 v153, v146 offset:2340
	ds_read_u16 v154, v146 offset:2600
	ds_read_u16 v155, v146 offset:2860
	v_lshlrev_b32_e32 v147, 15, v144
	v_lshl_add_u32 v147, v145, 4, v147
	s_waitcnt lgkmcnt(0)
	v_lshl_or_b32 v156, v149, 16, v148
	v_lshl_or_b32 v157, v151, 16, v150
	v_lshl_or_b32 v158, v153, 16, v152
	v_lshl_or_b32 v159, v155, 16, v154
	global_store_dwordx4 v147, v[156:159], s[4:5]
